# LoraUp GEMMs (P5 w/a, P7 g): skip the structurally-zero K tiles of the block-packed LoRA-up weight (K 256->128)
# speedup vs baseline: 1.0071x; 1.0010x over previous
.LBB0_465:
	s_ashr_i32 s35, s34, 31
	s_lshl_b64 s[36:37], s[34:35], 17
	s_add_u32 s36, s50, s36
	s_addc_u32 s37, s51, s37
	s_and_b64 s[38:39], s[2:3], exec
	s_cselect_b32 s49, s37, s43
	s_cselect_b32 s48, s36, s42
	s_ashr_i32 s31, s30, 31
	s_lshl_b64 s[38:39], s[30:31], 17
	s_add_u32 s38, s52, s38
	s_addc_u32 s39, s53, s39
	s_and_b64 s[46:47], s[2:3], exec
	s_cselect_b32 s47, s39, s45
	s_cselect_b32 s46, s38, s44
	s_add_u32 s68, s42, 0x10080
	s_addc_u32 s69, s43, 0
	v_lshl_add_u64 v[64:65], s[68:69], 0, v[128:129]
	v_lshl_add_u64 v[64:65], s[68:69], 0, v[132:133]
	s_add_i32 s41, s62, s54
	v_lshl_add_u64 v[214:215], s[44:45], 0, v[130:131]
	s_add_i32 s5, s41, 0x2000
	v_lshl_add_u64 v[144:145], v[214:215], 0, s[18:19]
	v_lshl_add_u64 v[216:217], s[44:45], 0, v[134:135]
	s_add_u32 s68, s44, 0x10100
	v_lshl_add_u64 v[144:145], v[216:217], 0, s[18:19]
	s_addc_u32 s69, s45, 0
	s_add_i32 s31, s63, s54
	v_lshl_add_u64 v[144:145], s[68:69], 0, v[130:131]
	s_add_i32 s35, s31, 0x2000
	v_lshl_add_u64 v[144:145], s[68:69], 0, v[134:135]
	v_lshl_add_u64 v[218:219], s[42:43], 0, v[128:129]
	v_lshl_add_u64 v[144:145], v[218:219], 0, s[18:19]
	v_lshl_add_u64 v[220:221], s[42:43], 0, v[132:133]
	v_lshl_add_u64 v[144:145], v[220:221], 0, s[18:19]
	s_add_i32 s67, 0, 0x18000
	s_add_i32 s80, 0, 0x1c000
	v_add_u32_e32 v136, s67, v152
	v_add_u32_e32 v142, s80, v152
	s_add_u32 s68, s42, 0x10100
	s_addc_u32 s69, s43, 0
	v_lshl_add_u64 v[222:223], s[68:69], 0, v[128:129]
	v_lshl_add_u64 v[222:223], s[68:69], 0, v[132:133]
	s_add_i32 s68, s67, s54
	s_add_i32 s67, s68, 0x2000
	v_lshl_add_u64 v[214:215], v[214:215], 0, s[20:21]
	s_add_u32 s78, s44, 0x10180
	v_lshl_add_u64 v[214:215], v[216:217], 0, s[20:21]
	s_addc_u32 s79, s45, 0
	s_add_i32 s44, s80, s54
	v_lshl_add_u64 v[214:215], s[78:79], 0, v[130:131]
	s_add_i32 s45, s44, 0x2000
	v_lshl_add_u64 v[214:215], s[78:79], 0, v[134:135]
	v_lshl_add_u64 v[214:215], v[218:219], 0, s[20:21]
	v_lshl_add_u64 v[214:215], v[220:221], 0, s[20:21]
	ds_read_b128 v[104:107], v154
	ds_read_b128 v[108:111], v154 offset:1024
	ds_read_b128 v[112:115], v154 offset:2048
	ds_read_b128 v[116:119], v154 offset:3072
	ds_read_b128 v[120:123], v155
	ds_read_b128 v[124:127], v155 offset:1024
	ds_read_b128 v[174:177], v155 offset:2048
	ds_read_b128 v[178:181], v155 offset:3072
	s_add_u32 s42, s42, 0x10080
	s_addc_u32 s43, s43, 0
	s_mov_b32 m0, s64
	v_lshl_add_u64 v[214:215], s[42:43], 0, v[128:129]
	ds_read_b128 v[182:185], v156
	ds_read_b128 v[186:189], v156 offset:1024
	ds_read_b128 v[190:193], v156 offset:2048
	ds_read_b128 v[194:197], v156 offset:3072
	ds_read_b128 v[198:201], v156 offset:4096
	ds_read_b128 v[202:205], v156 offset:5120
	ds_read_b128 v[206:209], v156 offset:6144
	ds_read_b128 v[210:213], v156 offset:7168
	global_load_lds_dwordx4 v[214:215], off
	v_lshl_add_u64 v[214:215], s[42:43], 0, v[132:133]
	s_mov_b32 m0, s65
	s_nop 0
	global_load_lds_dwordx4 v[214:215], off
	s_waitcnt vmcnt(8)
	s_waitcnt lgkmcnt(0)
	s_barrier
	s_setprio 1
	s_waitcnt lgkmcnt(0)
	v_mfma_f32_16x16x32_bf16 v[64:67], v[104:107], v[182:185], 0
	v_mfma_f32_16x16x32_bf16 v[68:71], v[112:115], v[182:185], 0
	v_mfma_f32_16x16x32_bf16 v[72:75], v[104:107], v[190:193], 0
	v_mfma_f32_16x16x32_bf16 v[76:79], v[112:115], v[190:193], 0
	v_mfma_f32_16x16x32_bf16 v[80:83], v[104:107], v[198:201], 0
	v_mfma_f32_16x16x32_bf16 v[84:87], v[112:115], v[198:201], 0
	v_mfma_f32_16x16x32_bf16 v[88:91], v[104:107], v[206:209], 0
	v_mfma_f32_16x16x32_bf16 v[64:67], v[108:111], v[186:189], v[64:67]
	v_mfma_f32_16x16x32_bf16 v[68:71], v[116:119], v[186:189], v[68:71]
	v_mfma_f32_16x16x32_bf16 v[72:75], v[108:111], v[194:197], v[72:75]
	v_mfma_f32_16x16x32_bf16 v[76:79], v[116:119], v[194:197], v[76:79]
	v_mfma_f32_16x16x32_bf16 v[80:83], v[108:111], v[202:205], v[80:83]
	v_mfma_f32_16x16x32_bf16 v[84:87], v[116:119], v[202:205], v[84:87]
	v_mfma_f32_16x16x32_bf16 v[214:217], v[108:111], v[210:213], v[88:91]
	v_mfma_f32_16x16x32_bf16 v[88:91], v[112:115], v[206:209], 0
	v_mfma_f32_16x16x32_bf16 v[218:221], v[116:119], v[210:213], v[88:91]
	s_setprio 0
	s_setprio 1
	v_mfma_f32_16x16x32_bf16 v[88:91], v[120:123], v[182:185], 0
	v_mfma_f32_16x16x32_bf16 v[32:35], v[174:177], v[182:185], 0
	v_mfma_f32_16x16x32_bf16 v[36:39], v[120:123], v[190:193], 0
	v_mfma_f32_16x16x32_bf16 v[40:43], v[174:177], v[190:193], 0
	v_mfma_f32_16x16x32_bf16 v[44:47], v[120:123], v[198:201], 0
	v_mfma_f32_16x16x32_bf16 v[48:51], v[174:177], v[198:201], 0
	v_mfma_f32_16x16x32_bf16 v[52:55], v[120:123], v[206:209], 0
	v_mfma_f32_16x16x32_bf16 v[56:59], v[174:177], v[206:209], 0
	v_mfma_f32_16x16x32_bf16 v[96:99], v[124:127], v[186:189], v[88:91]
	v_mfma_f32_16x16x32_bf16 v[32:35], v[178:181], v[186:189], v[32:35]
	v_mfma_f32_16x16x32_bf16 v[36:39], v[124:127], v[194:197], v[36:39]
	v_mfma_f32_16x16x32_bf16 v[40:43], v[178:181], v[194:197], v[40:43]
	v_mfma_f32_16x16x32_bf16 v[44:47], v[124:127], v[202:205], v[44:47]
	v_mfma_f32_16x16x32_bf16 v[48:51], v[178:181], v[202:205], v[48:51]
	v_mfma_f32_16x16x32_bf16 v[52:55], v[124:127], v[210:213], v[52:55]
	v_mfma_f32_16x16x32_bf16 v[56:59], v[178:181], v[210:213], v[56:59]
	s_setprio 0
	s_barrier
	s_mov_b32 m0, s41
	v_lshl_add_u64 v[250:251], s[46:47], 0, v[130:131]
	s_add_u32 s42, s46, 0x10000
	ds_read_b128 v[88:91], v156 offset:16384
	ds_read_b128 v[92:95], v156 offset:17408
	ds_read_b128 v[182:185], v156 offset:18432
	ds_read_b128 v[186:189], v156 offset:19456
	ds_read_b128 v[190:193], v156 offset:20480
	ds_read_b128 v[194:197], v156 offset:21504
	ds_read_b128 v[198:201], v156 offset:22528
	ds_read_b128 v[202:205], v156 offset:23552
	global_load_lds_dwordx4 v[250:251], off
	v_lshl_add_u64 v[252:253], s[46:47], 0, v[134:135]
	s_mov_b32 m0, s5
	s_addc_u32 s43, s47, 0
	global_load_lds_dwordx4 v[252:253], off
	v_lshl_add_u64 v[206:207], s[42:43], 0, v[130:131]
	s_mov_b32 m0, s31
	v_lshl_add_u64 v[138:139], s[48:49], 0, v[128:129]
	global_load_lds_dwordx4 v[206:207], off
	v_lshl_add_u64 v[206:207], s[42:43], 0, v[134:135]
	s_mov_b32 m0, s35
	v_lshl_add_u64 v[140:141], s[48:49], 0, v[132:133]
	global_load_lds_dwordx4 v[206:207], off
	s_mov_b32 m0, s55
	s_nop 0
	global_load_lds_dwordx4 v[138:139], off
	s_mov_b32 m0, s56
	s_nop 0
	global_load_lds_dwordx4 v[140:141], off
	s_waitcnt vmcnt(8)
	s_waitcnt lgkmcnt(0)
	s_barrier
	s_setprio 1
	s_waitcnt lgkmcnt(0)
	v_mfma_f32_16x16x32_bf16 v[0:3], v[104:107], v[198:201], 0
	v_mfma_f32_16x16x32_bf16 v[4:7], v[112:115], v[198:201], 0
	v_mfma_f32_16x16x32_bf16 v[144:147], v[104:107], v[88:91], 0
	v_mfma_f32_16x16x32_bf16 v[148:151], v[112:115], v[88:91], 0
	v_mfma_f32_16x16x32_bf16 v[158:161], v[104:107], v[182:185], 0
	v_mfma_f32_16x16x32_bf16 v[162:165], v[112:115], v[182:185], 0
	v_mfma_f32_16x16x32_bf16 v[166:169], v[104:107], v[190:193], 0
	v_mfma_f32_16x16x32_bf16 v[170:173], v[112:115], v[190:193], 0
	v_mfma_f32_16x16x32_bf16 v[0:3], v[108:111], v[202:205], v[0:3]
	v_mfma_f32_16x16x32_bf16 v[4:7], v[116:119], v[202:205], v[4:7]
	v_mfma_f32_16x16x32_bf16 v[144:147], v[108:111], v[92:95], v[144:147]
	v_mfma_f32_16x16x32_bf16 v[148:151], v[116:119], v[92:95], v[148:151]
	v_mfma_f32_16x16x32_bf16 v[158:161], v[108:111], v[186:189], v[158:161]
	v_mfma_f32_16x16x32_bf16 v[162:165], v[116:119], v[186:189], v[162:165]
	v_mfma_f32_16x16x32_bf16 v[166:169], v[108:111], v[194:197], v[166:169]
	v_mfma_f32_16x16x32_bf16 v[170:173], v[116:119], v[194:197], v[170:173]
	s_setprio 0
	s_setprio 1
	v_mfma_f32_16x16x32_bf16 v[8:11], v[120:123], v[88:91], 0
	v_mfma_f32_16x16x32_bf16 v[206:209], v[124:127], v[92:95], v[8:11]
	v_mfma_f32_16x16x32_bf16 v[8:11], v[174:177], v[88:91], 0
	v_mfma_f32_16x16x32_bf16 v[210:213], v[178:181], v[92:95], v[8:11]
	v_mfma_f32_16x16x32_bf16 v[8:11], v[120:123], v[182:185], 0
	v_mfma_f32_16x16x32_bf16 v[222:225], v[124:127], v[186:189], v[8:11]
	v_mfma_f32_16x16x32_bf16 v[8:11], v[174:177], v[182:185], 0
	v_mfma_f32_16x16x32_bf16 v[182:185], v[178:181], v[186:189], v[8:11]
	v_mfma_f32_16x16x32_bf16 v[8:11], v[120:123], v[190:193], 0
	v_mfma_f32_16x16x32_bf16 v[186:189], v[124:127], v[194:197], v[8:11]
	v_mfma_f32_16x16x32_bf16 v[8:11], v[174:177], v[190:193], 0
	v_mfma_f32_16x16x32_bf16 v[190:193], v[178:181], v[194:197], v[8:11]
	v_mfma_f32_16x16x32_bf16 v[8:11], v[120:123], v[198:201], 0
	v_mfma_f32_16x16x32_bf16 v[194:197], v[124:127], v[202:205], v[8:11]
	v_mfma_f32_16x16x32_bf16 v[8:11], v[174:177], v[198:201], 0
	v_mfma_f32_16x16x32_bf16 v[174:177], v[178:181], v[202:205], v[8:11]
	s_setprio 0
	s_barrier
	s_nop 4
	ds_read_b128 v[8:11], v136
	ds_read_b128 v[12:15], v136 offset:1024
	ds_read_b128 v[16:19], v136 offset:2048
	ds_read_b128 v[20:23], v136 offset:3072
	ds_read_b128 v[178:181], v142
	ds_read_b128 v[198:201], v142 offset:1024
	ds_read_b128 v[202:205], v142 offset:2048
	ds_read_b128 v[226:229], v142 offset:3072
	s_add_u32 s42, s48, 0x10000
	s_addc_u32 s43, s49, 0
	s_mov_b32 m0, s57
	v_lshl_add_u64 v[88:89], s[42:43], 0, v[128:129]
	ds_read_b128 v[24:27], v156 offset:32768
	ds_read_b128 v[28:31], v156 offset:33792
	ds_read_b128 v[60:63], v156 offset:34816
	ds_read_b128 v[230:233], v156 offset:35840
	ds_read_b128 v[234:237], v156 offset:36864
	ds_read_b128 v[238:241], v156 offset:37888
	ds_read_b128 v[242:245], v156 offset:38912
	ds_read_b128 v[246:249], v156 offset:39936
	global_load_lds_dwordx4 v[88:89], off
	v_lshl_add_u64 v[88:89], s[42:43], 0, v[132:133]
	s_mov_b32 m0, s58
	s_nop 0
	global_load_lds_dwordx4 v[88:89], off
	s_waitcnt vmcnt(8)
	s_waitcnt lgkmcnt(0)
	s_barrier
	s_setprio 1
	s_waitcnt lgkmcnt(0)
	v_mfma_f32_16x16x32_bf16 v[64:67], v[8:11], v[24:27], v[64:67]
	v_mfma_f32_16x16x32_bf16 v[124:127], v[12:15], v[28:31], v[64:67]
	v_mfma_f32_16x16x32_bf16 v[64:67], v[16:19], v[24:27], v[68:71]
	v_mfma_f32_16x16x32_bf16 v[120:123], v[20:23], v[28:31], v[64:67]
	v_mfma_f32_16x16x32_bf16 v[64:67], v[8:11], v[60:63], v[72:75]
	v_mfma_f32_16x16x32_bf16 v[108:111], v[12:15], v[230:233], v[64:67]
	v_mfma_f32_16x16x32_bf16 v[64:67], v[16:19], v[60:63], v[76:79]
	v_mfma_f32_16x16x32_bf16 v[104:107], v[20:23], v[230:233], v[64:67]
	v_mfma_f32_16x16x32_bf16 v[64:67], v[8:11], v[234:237], v[80:83]
	v_mfma_f32_16x16x32_bf16 v[92:95], v[12:15], v[238:241], v[64:67]
	v_mfma_f32_16x16x32_bf16 v[64:67], v[16:19], v[234:237], v[84:87]
	v_mfma_f32_16x16x32_bf16 v[88:91], v[20:23], v[238:241], v[64:67]
	v_mfma_f32_16x16x32_bf16 v[64:67], v[8:11], v[242:245], v[214:217]
	v_mfma_f32_16x16x32_bf16 v[76:79], v[12:15], v[246:249], v[64:67]
	v_mfma_f32_16x16x32_bf16 v[64:67], v[16:19], v[242:245], v[218:221]
	v_mfma_f32_16x16x32_bf16 v[72:75], v[20:23], v[246:249], v[64:67]
	s_setprio 0
	s_setprio 1
	v_mfma_f32_16x16x32_bf16 v[64:67], v[178:181], v[24:27], v[96:99]
	v_mfma_f32_16x16x32_bf16 v[24:27], v[202:205], v[24:27], v[32:35]
	v_mfma_f32_16x16x32_bf16 v[112:115], v[226:229], v[28:31], v[24:27]
	v_mfma_f32_16x16x32_bf16 v[24:27], v[178:181], v[60:63], v[36:39]
	v_mfma_f32_16x16x32_bf16 v[100:103], v[198:201], v[230:233], v[24:27]
	v_mfma_f32_16x16x32_bf16 v[24:27], v[202:205], v[60:63], v[40:43]
	v_mfma_f32_16x16x32_bf16 v[96:99], v[226:229], v[230:233], v[24:27]
	v_mfma_f32_16x16x32_bf16 v[24:27], v[178:181], v[234:237], v[44:47]
	v_mfma_f32_16x16x32_bf16 v[84:87], v[198:201], v[238:241], v[24:27]
	v_mfma_f32_16x16x32_bf16 v[24:27], v[202:205], v[234:237], v[48:51]
	v_mfma_f32_16x16x32_bf16 v[80:83], v[226:229], v[238:241], v[24:27]
	v_mfma_f32_16x16x32_bf16 v[24:27], v[178:181], v[242:245], v[52:55]
	v_mfma_f32_16x16x32_bf16 v[68:71], v[198:201], v[246:249], v[24:27]
	v_mfma_f32_16x16x32_bf16 v[24:27], v[202:205], v[242:245], v[56:59]
	v_mfma_f32_16x16x32_bf16 v[116:119], v[198:201], v[28:31], v[64:67]
	v_mfma_f32_16x16x32_bf16 v[64:67], v[226:229], v[246:249], v[24:27]
	s_setprio 0
	s_barrier
	s_mov_b32 m0, s68
	s_nop 2
	v_lshl_add_u64 v[24:25], v[250:251], 0, s[12:13]
	s_add_u32 s42, s46, 0x10080
	ds_read_b128 v[32:35], v156 offset:49152
	ds_read_b128 v[36:39], v156 offset:50176
	ds_read_b128 v[214:217], v156 offset:51200
	ds_read_b128 v[218:221], v156 offset:52224
	ds_read_b128 v[230:233], v156 offset:53248
	ds_read_b128 v[234:237], v156 offset:54272
	ds_read_b128 v[238:241], v156 offset:55296
	ds_read_b128 v[242:245], v156 offset:56320
	global_load_lds_dwordx4 v[24:25], off
	v_lshl_add_u64 v[24:25], v[252:253], 0, s[12:13]
	s_mov_b32 m0, s67
	s_addc_u32 s43, s47, 0
	global_load_lds_dwordx4 v[24:25], off
	v_lshl_add_u64 v[24:25], s[42:43], 0, v[130:131]
	s_mov_b32 m0, s44
	s_nop 0
	global_load_lds_dwordx4 v[24:25], off
	v_lshl_add_u64 v[24:25], s[42:43], 0, v[134:135]
	s_mov_b32 m0, s45
	s_nop 0
	global_load_lds_dwordx4 v[24:25], off
	v_lshl_add_u64 v[24:25], v[138:139], 0, s[12:13]
	s_mov_b32 m0, s59
	s_nop 0
	global_load_lds_dwordx4 v[24:25], off
	v_lshl_add_u64 v[24:25], v[140:141], 0, s[12:13]
	s_mov_b32 m0, s60
	s_nop 0
	global_load_lds_dwordx4 v[24:25], off
	s_waitcnt vmcnt(8)
	s_waitcnt lgkmcnt(0)
	s_barrier
	s_setprio 1
	s_waitcnt lgkmcnt(0)
	v_mfma_f32_16x16x32_bf16 v[24:27], v[8:11], v[32:35], v[144:147]
	v_mfma_f32_16x16x32_bf16 v[60:63], v[12:15], v[36:39], v[24:27]
	v_mfma_f32_16x16x32_bf16 v[24:27], v[16:19], v[32:35], v[148:151]
	v_mfma_f32_16x16x32_bf16 v[56:59], v[20:23], v[36:39], v[24:27]
	v_mfma_f32_16x16x32_bf16 v[24:27], v[8:11], v[214:217], v[158:161]
	v_mfma_f32_16x16x32_bf16 v[44:47], v[12:15], v[218:221], v[24:27]
	v_mfma_f32_16x16x32_bf16 v[24:27], v[16:19], v[214:217], v[162:165]
	v_mfma_f32_16x16x32_bf16 v[40:43], v[20:23], v[218:221], v[24:27]
	v_mfma_f32_16x16x32_bf16 v[24:27], v[8:11], v[230:233], v[166:169]
	v_mfma_f32_16x16x32_bf16 v[0:3], v[8:11], v[238:241], v[0:3]
	v_mfma_f32_16x16x32_bf16 v[28:31], v[12:15], v[234:237], v[24:27]
	v_mfma_f32_16x16x32_bf16 v[24:27], v[16:19], v[230:233], v[170:173]
	v_mfma_f32_16x16x32_bf16 v[12:15], v[12:15], v[242:245], v[0:3]
	v_mfma_f32_16x16x32_bf16 v[0:3], v[16:19], v[238:241], v[4:7]
	v_mfma_f32_16x16x32_bf16 v[24:27], v[20:23], v[234:237], v[24:27]
	v_mfma_f32_16x16x32_bf16 v[8:11], v[20:23], v[242:245], v[0:3]
	s_setprio 0
	s_setprio 1
	v_mfma_f32_16x16x32_bf16 v[0:3], v[178:181], v[32:35], v[206:209]
	v_mfma_f32_16x16x32_bf16 v[52:55], v[198:201], v[36:39], v[0:3]
	v_mfma_f32_16x16x32_bf16 v[0:3], v[202:205], v[32:35], v[210:213]
	v_mfma_f32_16x16x32_bf16 v[48:51], v[226:229], v[36:39], v[0:3]
	v_mfma_f32_16x16x32_bf16 v[0:3], v[178:181], v[214:217], v[222:225]
	v_mfma_f32_16x16x32_bf16 v[36:39], v[198:201], v[218:221], v[0:3]
	v_mfma_f32_16x16x32_bf16 v[0:3], v[202:205], v[214:217], v[182:185]
	v_mfma_f32_16x16x32_bf16 v[32:35], v[226:229], v[218:221], v[0:3]
	v_mfma_f32_16x16x32_bf16 v[0:3], v[178:181], v[230:233], v[186:189]
	v_mfma_f32_16x16x32_bf16 v[20:23], v[198:201], v[234:237], v[0:3]
	v_mfma_f32_16x16x32_bf16 v[0:3], v[202:205], v[230:233], v[190:193]
	v_mfma_f32_16x16x32_bf16 v[16:19], v[226:229], v[234:237], v[0:3]
	v_mfma_f32_16x16x32_bf16 v[0:3], v[178:181], v[238:241], v[194:197]
	v_mfma_f32_16x16x32_bf16 v[4:7], v[198:201], v[242:245], v[0:3]
	v_mfma_f32_16x16x32_bf16 v[0:3], v[202:205], v[238:241], v[174:177]
	v_mfma_f32_16x16x32_bf16 v[0:3], v[226:229], v[242:245], v[0:3]
	s_setprio 0
	s_barrier
	s_andn2_b64 vcc, exec, s[14:15]
	s_cbranch_vccnz .LBB0_467
	s_barrier

.LBB0_773:
	s_andn2_b64 vcc, exec, s[10:11]
	s_cbranch_vccnz .LBB0_823
	v_ashrrev_i32_e32 v2, 31, v0
	v_lshrrev_b32_e32 v2, 26, v2
	v_lshlrev_b32_e32 v1, 4, v0
	v_add_u32_e32 v2, v0, v2
	v_bfe_i32 v0, v0, 27, 1
	v_lshrrev_b32_e32 v0, 22, v0
	v_add_u32_e32 v0, v1, v0
	v_and_b32_e32 v0, 0xfffffc00, v0
	v_sub_u32_e32 v0, v1, v0
	v_lshrrev_b32_e32 v3, 4, v0
	v_bitop3_b32 v0, v3, v0, 32 bitop3:0x6c
	v_ashrrev_i32_e32 v4, 31, v0
	v_ashrrev_i32_e32 v2, 6, v2
	v_lshrrev_b32_e32 v4, 26, v4
	v_lshlrev_b32_e32 v3, 3, v2
	v_add_u32_e32 v4, v0, v4
	v_and_b32_e32 v3, -16, v3
	v_ashrrev_i32_e32 v5, 6, v4
	v_and_b32_e32 v4, 0xc0, v4
	v_add_u32_e32 v3, v5, v3
	v_sub_u32_e32 v0, v0, v4
	v_mov_b32_e32 v4, 1
	v_lshlrev_b32_e32 v2, 5, v2
	v_ashrrev_i16_sdwa v0, v4, sext(v0) dst_sel:DWORD dst_unused:UNUSED_PAD src0_sel:DWORD src1_sel:BYTE_0
	v_lshlrev_b32_e32 v6, 1, v3
	v_lshrrev_b32_e32 v7, 2, v3
	v_and_b32_e32 v5, 3, v5
	s_mov_b32 s3, 0x7fffe0
	v_and_b32_e32 v2, 32, v2
	v_bfe_i32 v0, v0, 0, 16
	v_and_b32_e32 v6, 24, v6
	v_and_b32_e32 v7, 4, v7
	v_and_or_b32 v5, v3, s3, v5
	v_or3_b32 v5, v5, v7, v6
	v_add_lshl_u32 v0, v2, v0, 1
	v_lshl_add_u32 v128, v3, 9, v0
	v_lshl_add_u32 v130, v5, 9, v0
	v_add_u32_e32 v0, 0x2000, v1
	v_ashrrev_i32_e32 v1, 31, v0
	v_lshrrev_b32_e32 v1, 22, v1
	v_add_u32_e32 v1, v0, v1
	v_ashrrev_i32_e32 v1, 10, v1
	v_mul_i32_i24_e32 v2, 0x400, v1
	v_sub_u32_e32 v0, v0, v2
	v_lshrrev_b32_e32 v2, 4, v0
	v_bitop3_b32 v0, v2, v0, 32 bitop3:0x6c
	v_ashrrev_i32_e32 v3, 31, v0
	v_lshrrev_b32_e32 v3, 26, v3
	s_add_u32 s50, s70, 0x19c00100
	v_lshlrev_b32_e32 v2, 3, v1
	v_add_u32_e32 v3, v0, v3
	s_addc_u32 s51, s71, 0
	v_and_b32_e32 v2, -16, v2
	v_ashrrev_i32_e32 v5, 6, v3
	s_add_u32 s52, s70, 0x5400100
	v_add_u32_e32 v2, v5, v2
	v_and_b32_e32 v5, 3, v5
	s_addc_u32 s53, s71, 0
	v_and_or_b32 v5, v2, s3, v5
	s_ashr_i32 s3, s14, 6
	s_ashr_i32 s5, s4, 31
	s_ashr_i32 s41, s40, 31
	s_ashr_i32 s2, s14, 8
	v_and_b32_e32 v3, 0xc0, v3
	s_lshl_b32 s54, s3, 10
	s_lshl_b64 s[10:11], s[4:5], 17
	s_lshl_b64 s[12:13], s[40:41], 17
	v_sub_u32_e32 v0, v0, v3
	s_add_u32 s44, s52, s12
	v_lshlrev_b32_e32 v1, 5, v1
	v_ashrrev_i16_sdwa v0, v4, sext(v0) dst_sel:DWORD dst_unused:UNUSED_PAD src0_sel:DWORD src1_sel:BYTE_0
	v_lshlrev_b32_e32 v3, 1, v2
	v_lshrrev_b32_e32 v4, 2, v2
	s_addc_u32 s45, s53, s13
	s_add_i32 s55, s54, 0
	v_and_b32_e32 v1, 32, v1
	v_bfe_i32 v0, v0, 0, 16
	v_and_b32_e32 v3, 24, v3
	v_and_b32_e32 v4, 4, v4
	s_add_i32 m0, s55, 0x10000
	v_or3_b32 v3, v5, v4, v3
	v_add_lshl_u32 v0, v1, v0, 1
	global_load_lds_dwordx4 v130, s[44:45]
	s_add_i32 m0, s55, 0x12000
	v_lshl_add_u32 v134, v3, 9, v0
	s_add_u32 s12, s44, 0x10000
	global_load_lds_dwordx4 v134, s[44:45]
	s_addc_u32 s13, s45, 0
	s_add_i32 m0, s55, 0x14000
	v_lshl_add_u32 v132, v2, 9, v0
	global_load_lds_dwordx4 v130, s[12:13]
	s_add_i32 m0, s55, 0x16000
	s_add_u32 s42, s50, s10
	s_addc_u32 s43, s51, s11
	s_add_i32 s56, s55, 0x2000
	global_load_lds_dwordx4 v134, s[12:13]
	s_mov_b32 m0, s55
	s_add_u32 s10, s42, 0x10000
	global_load_lds_dwordx4 v128, s[42:43]
	s_mov_b32 m0, s56
	s_addc_u32 s11, s43, 0
	s_add_i32 s57, s55, 0x4000
	global_load_lds_dwordx4 v132, s[42:43]
	s_mov_b32 m0, s57
	s_add_i32 s58, s55, 0x6000
	global_load_lds_dwordx4 v128, s[10:11]
	s_mov_b32 m0, s58
	v_mov_b32_e32 v137, 0
	global_load_lds_dwordx4 v132, s[10:11]
	v_mov_b32_e32 v131, v137
	v_mov_b32_e32 v135, v137
	v_mov_b32_e32 v129, v137
	v_mov_b32_e32 v133, v137
	s_cmp_eq_u32 s2, 1
	v_lshl_add_u64 v[6:7], s[44:45], 0, v[130:131]
	v_lshl_add_u64 v[4:5], s[44:45], 0, v[134:135]
	v_lshl_add_u64 v[0:1], s[42:43], 0, v[128:129]
	s_cselect_b64 s[10:11], -1, 0
	s_cmp_lg_u32 s2, 1
	v_lshl_add_u64 v[2:3], s[42:43], 0, v[132:133]
	s_cbranch_scc1 .LBB0_776
	s_barrier
